# combination: peeled first GEMM iteration + top-level-generation barrier polling + cross-trip DIFF combine prefetch, on the G2-rebalanced version
# speedup vs baseline: 1.0113x; 1.0031x over previous
.LBB0_708:
	v_mov_b32_e32 v16, v244
	s_waitcnt vmcnt(0) lgkmcnt(0)
	s_waitcnt vmcnt(0)
	v_mov_b32_e32 v5, v1
	v_and_b32_e32 v0, 63, v16
	v_lshlrev_b32_e32 v0, 2, v0
	global_load_dword v2, v0, s[8:9]
	global_load_dword v3, v0, s[8:9] offset:256
	v_readlane_b32 s52, v253, 0
	v_readlane_b32 s53, v253, 1
	s_mov_b64 s[48:49], s[52:53]
	s_lshl_b64 s[4:5], s[16:17], 11
	s_ashr_i32 s15, s14, 31
	v_readlane_b32 s7, v255, 5
	s_add_u32 s7, s7, s22
	v_readlane_b32 s54, v253, 2
	v_readlane_b32 s55, v253, 3
	v_readlane_b32 s56, v253, 4
	v_readlane_b32 s57, v253, 5
	v_readlane_b32 s58, v253, 6
	v_readlane_b32 s59, v253, 7
	s_mov_b64 s[52:53], s[56:57]
	s_mov_b64 s[54:55], s[58:59]
	s_mov_b32 s6, 8
	s_waitcnt vmcnt(0)
	v_mul_f32_e32 v4, v2, v3
	s_nop 1
	v_mov_b32_dpp v5, v4 quad_perm:[1,0,3,2] row_mask:0xf bank_mask:0xf
	v_fmac_f32_e32 v5, v2, v3
	s_nop 1
	v_add_f32_dpp v2, v5, v5 quad_perm:[2,3,0,1] row_mask:0xf bank_mask:0xf bound_ctrl:1
	v_mov_b32_e32 v5, v1
	s_nop 0
	v_add_f32_dpp v2, v2, v2 row_half_mirror row_mask:0xf bank_mask:0xf bound_ctrl:1
	s_nop 1
	v_add_f32_dpp v2, v2, v2 row_mirror row_mask:0xf bank_mask:0xf bound_ctrl:1
	v_mov_b32_e32 v3, v2
	s_nop 1
	v_permlane16_swap_b32_e32 v2, v3
	v_add_f32_e32 v2, v2, v3
	v_mov_b32_e32 v3, v2
	s_nop 1
	v_permlane32_swap_b32_e32 v2, v3
	v_add_f32_e32 v2, v2, v3
	global_load_dword v3, v0, s[8:9] offset:512
	s_nop 0
	global_load_dword v0, v0, s[8:9] offset:768
	v_mul_f32_e32 v2, 0x3fb8aa3b, v2
	v_exp_f32_e32 v2, v2
	s_waitcnt vmcnt(0)
	v_mul_f32_e32 v4, v3, v0
	s_nop 1
	v_mov_b32_dpp v5, v4 quad_perm:[1,0,3,2] row_mask:0xf bank_mask:0xf
	v_fmac_f32_e32 v5, v3, v0
	s_nop 1
	v_add_f32_dpp v0, v5, v5 quad_perm:[2,3,0,1] row_mask:0xf bank_mask:0xf bound_ctrl:1
	s_nop 1
	v_add_f32_dpp v0, v0, v0 row_half_mirror row_mask:0xf bank_mask:0xf bound_ctrl:1
	s_nop 1
	v_add_f32_dpp v0, v0, v0 row_mirror row_mask:0xf bank_mask:0xf bound_ctrl:1
	v_mov_b32_e32 v3, v0
	s_nop 1
	v_permlane16_swap_b32_e32 v0, v3
	v_add_f32_e32 v0, v0, v3
	v_mov_b32_e32 v3, v0
	s_nop 1
	v_permlane32_swap_b32_e32 v0, v3
	v_add_f32_e32 v0, v0, v3
	v_mul_f32_e32 v0, 0x3fb8aa3b, v0
	v_exp_f32_e32 v0, v0
	s_nop 0
	v_sub_f32_e32 v0, v2, v0
	v_add_f32_e32 v6, v152, v0
	v_lshlrev_b32_e32 v0, 3, v16
	v_and_b32_e32 v0, 0x78, v0
	v_or_b32_e32 v0, s64, v0
	v_lshl_add_u64 v[8:9], v[0:1], 2, s[48:49]
	global_load_dwordx4 v[2:5], v[8:9], off offset:16
	s_nop 0
	global_load_dwordx4 v[8:11], v[8:9], off
	v_ashrrev_i32_e32 v0, 1, v16
	v_mov_b32_e32 v7, v6
	s_waitcnt vmcnt(1)
	v_pk_mul_f32 v[12:13], v[130:131], v[2:3]
	v_bfe_u32 v2, v16, 4, 2
	v_mov_b32_e32 v3, v1
	v_pk_mul_f32 v[14:15], v[130:131], v[4:5]
	v_and_b32_e32 v4, 0xffffffe0, v0
	v_lshl_add_u64 v[2:3], v[2:3], 0, s[14:15]
	v_readlane_b32 s14, v255, 6
	v_ashrrev_i32_e32 v5, 31, v4
	s_addc_u32 s14, s14, 0
	v_lshl_add_u64 v[2:3], v[2:3], 0, v[4:5]
	s_add_u32 s10, s7, s10
	v_lshlrev_b64 v[4:5], 13, v[2:3]
	s_addc_u32 s11, s14, s11
	s_lshl_b32 s7, s23, 9
	v_and_b32_e32 v0, 15, v16
	v_lshl_add_u64 v[16:17], s[10:11], 0, v[4:5]
	s_add_u32 s10, s54, s7
	v_lshlrev_b64 v[4:5], 11, v[2:3]
	s_addc_u32 s11, s55, 0
	v_readlane_b32 s7, v255, 7
	v_lshl_add_u64 v[4:5], s[12:13], 0, v[4:5]
	s_add_u32 s12, s7, s22
	v_readlane_b32 s7, v255, 8
	s_addc_u32 s13, s7, 0
	v_lshl_add_u64 v[2:3], v[2:3], 0, s[4:5]
	v_readlane_b32 s4, v255, 9
	s_add_u32 s4, s4, s22
	v_readlane_b32 s5, v255, 10
	v_lshl_add_u64 v[18:19], s[10:11], 0, v[4:5]
	v_lshl_add_u64 v[20:21], s[12:13], 0, v[4:5]
	v_lshlrev_b64 v[4:5], 13, v[2:3]
	s_addc_u32 s5, s5, 0
	v_lshl_add_u64 v[22:23], s[4:5], 0, v[4:5]
	s_add_u32 s4, s80, s22
	v_lshlrev_b64 v[2:3], 11, v[2:3]
	s_addc_u32 s5, s83, 0
	s_waitcnt vmcnt(0)
	v_pk_mul_f32 v[8:9], v[130:131], v[8:9]
	v_pk_mul_f32 v[10:11], v[130:131], v[10:11]
	v_lshlrev_b32_e32 v0, 4, v0
	v_lshl_add_u64 v[24:25], s[10:11], 0, v[2:3]
	v_lshl_add_u64 v[26:27], s[4:5], 0, v[2:3]
	s_mov_b64 s[100:101], 0x27a0000
	v_lshl_add_u64 v[224:225], v[24:25], 0, v[0:1]
	v_lshl_add_u64 v[226:227], v[22:23], 0, v[0:1]
	v_lshl_add_u64 v[224:225], v[224:225], 0, s[100:101]
	global_load_dwordx4 v[208:211], v[224:225], off
	global_load_dwordx4 v[212:215], v[224:225], off offset:256
	global_load_dwordx4 v[216:219], v[226:227], off
	s_mov_b64 s[100:101], 0x27a2000
	v_lshl_add_u64 v[204:205], v[18:19], 0, v[0:1]
	v_lshl_add_u64 v[206:207], v[16:17], 0, v[0:1]
	v_lshl_add_u64 v[204:205], v[204:205], 0, s[100:101]
	global_load_dwordx4 v[192:195], v[204:205], off
	global_load_dwordx4 v[196:199], v[204:205], off offset:256
	global_load_dwordx4 v[200:203], v[206:207], off
.LBB0_709:
	v_lshl_add_u64 v[2:3], v[24:25], 0, v[0:1]
	v_add_co_u32_e32 v28, vcc, 0x27a0000, v2
	v_lshl_add_u64 v[32:33], v[22:23], 0, v[0:1]
	s_nop 0
	v_addc_co_u32_e32 v29, vcc, 0, v3, vcc
	s_waitcnt vmcnt(3)
	v_mov_b32_e32 v2, v208
	v_mov_b32_e32 v3, v209
	v_mov_b32_e32 v4, v210
	v_mov_b32_e32 v5, v211
	s_nop 0
	v_mov_b32_e32 v28, v212
	v_mov_b32_e32 v29, v213
	v_mov_b32_e32 v30, v214
	v_mov_b32_e32 v31, v215
	s_mov_b32 s4, 0x27a2000
	v_mov_b32_e32 v32, v216
	v_mov_b32_e32 v33, v217
	v_mov_b32_e32 v34, v218
	v_mov_b32_e32 v35, v219
	s_add_i32 s6, s6, -2
	v_lshl_add_u64 v[22:23], v[22:23], 0, s[24:25]
	v_lshl_add_u64 v[24:25], v[24:25], 0, s[42:43]
	s_cmp_lg_u32 s6, 0
	s_nop 0
	v_lshlrev_b32_e32 v36, 16, v5
	v_and_b32_e32 v37, 0xffff0000, v5
	s_nop 0
	v_lshlrev_b32_e32 v38, 16, v31
	v_and_b32_e32 v39, 0xffff0000, v31
	v_pk_fma_f32 v[36:37], v[6:7], v[38:39], v[36:37] neg_lo:[1,0,0] neg_hi:[1,0,0]
	v_lshlrev_b32_e32 v38, 16, v4
	v_and_b32_e32 v39, 0xffff0000, v4
	v_lshlrev_b32_e32 v4, 16, v30
	v_and_b32_e32 v5, 0xffff0000, v30
	v_pk_fma_f32 v[4:5], v[6:7], v[4:5], v[38:39] neg_lo:[1,0,0] neg_hi:[1,0,0]
	v_mov_b32_e32 v30, v36
	v_mov_b32_e32 v31, v4
	v_pk_mul_f32 v[30:31], v[30:31], v[30:31]
	v_mov_b32_e32 v38, v37
	v_mov_b32_e32 v39, v5
	v_pk_fma_f32 v[30:31], v[38:39], v[38:39], v[30:31]
	s_nop 0
	v_lshlrev_b32_e32 v38, 16, v34
	v_and_b32_e32 v39, 0xffff0000, v34
	v_mul_f32_e32 v34, 0xbfb8aa3b, v38
	v_exp_f32_e32 v34, v34
	v_lshlrev_b32_e32 v42, 16, v29
	v_and_b32_e32 v43, 0xffff0000, v29
	v_add_f32_e32 v34, 1.0, v34
	v_rcp_f32_e32 v40, v34
	v_mul_f32_e32 v34, 0xbfb8aa3b, v39
	v_exp_f32_e32 v34, v34
	s_nop 0
	v_add_f32_e32 v34, 1.0, v34
	v_rcp_f32_e32 v41, v34
	s_nop 0
	v_pk_mul_f32 v[38:39], v[40:41], v[38:39]
	v_lshlrev_b32_e32 v40, 16, v3
	v_and_b32_e32 v41, 0xffff0000, v3
	v_pk_fma_f32 v[40:41], v[6:7], v[42:43], v[40:41] neg_lo:[1,0,0] neg_hi:[1,0,0]
	v_lshlrev_b32_e32 v42, 16, v33
	v_mul_f32_e32 v3, 0xbfb8aa3b, v42
	v_exp_f32_e32 v3, v3
	v_and_b32_e32 v43, 0xffff0000, v33
	v_mov_b32_e32 v29, v40
	v_add_f32_e32 v3, 1.0, v3
	v_rcp_f32_e32 v44, v3
	v_mul_f32_e32 v3, 0xbfb8aa3b, v43
	v_exp_f32_e32 v3, v3
	s_nop 0
	v_add_f32_e32 v3, 1.0, v3
	v_rcp_f32_e32 v45, v3
	v_and_b32_e32 v3, 0xffff0000, v28
	v_pk_mul_f32 v[42:43], v[44:45], v[42:43]
	v_lshlrev_b32_e32 v44, 16, v2
	v_and_b32_e32 v45, 0xffff0000, v2
	v_lshlrev_b32_e32 v2, 16, v28
	v_pk_fma_f32 v[2:3], v[6:7], v[2:3], v[44:45] neg_lo:[1,0,0] neg_hi:[1,0,0]
	v_mov_b32_e32 v45, v41
	v_mov_b32_e32 v28, v2
	v_pk_mul_f32 v[28:29], v[28:29], v[28:29]
	v_mov_b32_e32 v44, v3
	v_pk_fma_f32 v[28:29], v[44:45], v[44:45], v[28:29]
	v_lshlrev_b32_e32 v44, 16, v32
	v_add_f32_e32 v28, v28, v29
	v_add_f32_e32 v28, v31, v28
	v_add_f32_e32 v28, v30, v28
	v_and_b32_e32 v45, 0xffff0000, v32
	v_mul_f32_e32 v32, 0xbfb8aa3b, v44
	v_add_f32_dpp v28, v28, v28 quad_perm:[1,0,3,2] row_mask:0xf bank_mask:0xf bound_ctrl:1
	v_mul_f32_e32 v33, 0xbfb8aa3b, v45
	v_exp_f32_e32 v32, v32
	v_add_f32_dpp v28, v28, v28 quad_perm:[2,3,0,1] row_mask:0xf bank_mask:0xf bound_ctrl:1
	v_exp_f32_e32 v33, v33
	v_add_f32_e32 v32, 1.0, v32
	v_add_f32_dpp v28, v28, v28 row_half_mirror row_mask:0xf bank_mask:0xf bound_ctrl:1
	v_add_f32_e32 v33, 1.0, v33
	v_rcp_f32_e32 v32, v32
	v_add_f32_dpp v28, v28, v28 row_mirror row_mask:0xf bank_mask:0xf bound_ctrl:1
	v_fmamk_f32 v28, v28, 0x3c000000, v245
	v_cmp_gt_f32_e32 vcc, s75, v28
	v_mul_f32_e32 v29, 0x4b800000, v28
	v_rcp_f32_e32 v33, v33
	v_cndmask_b32_e32 v28, v28, v29, vcc
	v_rsq_f32_e32 v28, v28
	v_pk_mul_f32 v[32:33], v[32:33], v[44:45]
	v_mul_f32_e32 v29, 0x45800000, v28
	v_cndmask_b32_e32 v28, v28, v29, vcc
	v_pk_mul_f32 v[2:3], v[2:3], v[28:29] op_sel_hi:[1,0]
	v_pk_mul_f32 v[30:31], v[40:41], v[28:29] op_sel_hi:[1,0]
	v_pk_mul_f32 v[2:3], v[8:9], v[2:3]
	v_pk_mul_f32 v[30:31], v[10:11], v[30:31]
	v_pk_mul_f32 v[4:5], v[4:5], v[28:29] op_sel_hi:[1,0]
	v_pk_mul_f32 v[2:3], v[32:33], v[2:3]
	v_pk_mul_f32 v[30:31], v[42:43], v[30:31]
	v_pk_mul_f32 v[4:5], v[12:13], v[4:5]
	v_cvt_pk_bf16_f32 v2, v2, v3
	v_cvt_pk_bf16_f32 v3, v30, v31
	v_pk_mul_f32 v[4:5], v[38:39], v[4:5]
	v_lshlrev_b32_e32 v30, 16, v35
	v_cvt_pk_bf16_f32 v4, v4, v5
	v_mul_f32_e32 v5, 0xbfb8aa3b, v30
	v_exp_f32_e32 v5, v5
	v_and_b32_e32 v31, 0xffff0000, v35
	v_pk_mul_f32 v[28:29], v[36:37], v[28:29] op_sel_hi:[1,0]
	v_add_f32_e32 v5, 1.0, v5
	v_rcp_f32_e32 v32, v5
	v_mul_f32_e32 v5, 0xbfb8aa3b, v31
	v_exp_f32_e32 v5, v5
	v_pk_mul_f32 v[28:29], v[14:15], v[28:29]
	v_add_f32_e32 v5, 1.0, v5
	v_rcp_f32_e32 v33, v5
	s_nop 0
	v_pk_mul_f32 v[30:31], v[32:33], v[30:31]
	s_nop 0
	v_pk_mul_f32 v[28:29], v[30:31], v[28:29]
	v_lshl_add_u64 v[32:33], v[16:17], 0, v[0:1]
	v_cvt_pk_bf16_f32 v5, v28, v29
	v_lshl_add_u64 v[28:29], v[26:27], 0, v[0:1]
	global_store_dwordx4 v[28:29], v[2:5], off
	v_lshl_add_u64 v[16:17], v[16:17], 0, s[24:25]
	v_lshl_add_u64 v[26:27], v[26:27], 0, s[42:43]
	v_lshl_add_u64 v[2:3], v[18:19], 0, v[0:1]
	v_add_co_u32_e32 v28, vcc, s4, v2
	v_lshl_add_u64 v[18:19], v[18:19], 0, s[42:43]
	s_nop 0
	v_addc_co_u32_e32 v29, vcc, 0, v3, vcc
	s_waitcnt vmcnt(1)
	v_mov_b32_e32 v2, v192
	v_mov_b32_e32 v3, v193
	v_mov_b32_e32 v4, v194
	v_mov_b32_e32 v5, v195
	s_nop 0
	v_mov_b32_e32 v28, v196
	v_mov_b32_e32 v29, v197
	v_mov_b32_e32 v30, v198
	v_mov_b32_e32 v31, v199
	s_nop 0
	v_lshlrev_b32_e32 v36, 16, v5
	v_mov_b32_e32 v32, v200
	v_mov_b32_e32 v33, v201
	v_mov_b32_e32 v34, v202
	v_mov_b32_e32 v35, v203
	s_cmp_lg_u32 s6, 0
	s_cbranch_scc0 .Ldc2_skip
	s_mov_b64 s[100:101], 0x27a0000
	v_lshl_add_u64 v[224:225], v[24:25], 0, v[0:1]
	v_lshl_add_u64 v[226:227], v[22:23], 0, v[0:1]
	v_lshl_add_u64 v[224:225], v[224:225], 0, s[100:101]
	global_load_dwordx4 v[208:211], v[224:225], off
	global_load_dwordx4 v[212:215], v[224:225], off offset:256
	global_load_dwordx4 v[216:219], v[226:227], off
	s_mov_b64 s[100:101], 0x27a2000
	v_lshl_add_u64 v[204:205], v[18:19], 0, v[0:1]
	v_lshl_add_u64 v[206:207], v[16:17], 0, v[0:1]
	v_lshl_add_u64 v[204:205], v[204:205], 0, s[100:101]
	global_load_dwordx4 v[192:195], v[204:205], off
	global_load_dwordx4 v[196:199], v[204:205], off offset:256
	global_load_dwordx4 v[200:203], v[206:207], off
.Ldc2_skip:
	v_and_b32_e32 v37, 0xffff0000, v5
	s_nop 0
	v_lshlrev_b32_e32 v38, 16, v31
	v_and_b32_e32 v39, 0xffff0000, v31
	v_pk_fma_f32 v[36:37], v[6:7], v[38:39], v[36:37] neg_lo:[1,0,0] neg_hi:[1,0,0]
	v_lshlrev_b32_e32 v38, 16, v4
	v_and_b32_e32 v39, 0xffff0000, v4
	v_lshlrev_b32_e32 v4, 16, v30
	v_and_b32_e32 v5, 0xffff0000, v30
	v_pk_fma_f32 v[4:5], v[6:7], v[4:5], v[38:39] neg_lo:[1,0,0] neg_hi:[1,0,0]
	v_mov_b32_e32 v30, v36
	v_mov_b32_e32 v31, v4
	v_pk_mul_f32 v[30:31], v[30:31], v[30:31]
	v_mov_b32_e32 v38, v37
	v_mov_b32_e32 v39, v5
	v_pk_fma_f32 v[30:31], v[38:39], v[38:39], v[30:31]
	v_lshlrev_b32_e32 v42, 16, v29
	v_and_b32_e32 v43, 0xffff0000, v29
	s_nop 0
	v_lshlrev_b32_e32 v38, 16, v34
	v_and_b32_e32 v39, 0xffff0000, v34
	v_mul_f32_e32 v34, 0xbfb8aa3b, v38
	v_exp_f32_e32 v34, v34
	s_nop 0
	v_add_f32_e32 v34, 1.0, v34
	v_rcp_f32_e32 v40, v34
	v_mul_f32_e32 v34, 0xbfb8aa3b, v39
	v_exp_f32_e32 v34, v34
	s_nop 0
	v_add_f32_e32 v34, 1.0, v34
	v_rcp_f32_e32 v41, v34
	s_nop 0
	v_pk_mul_f32 v[38:39], v[40:41], v[38:39]
	v_lshlrev_b32_e32 v40, 16, v3
	v_and_b32_e32 v41, 0xffff0000, v3
	v_pk_fma_f32 v[40:41], v[6:7], v[42:43], v[40:41] neg_lo:[1,0,0] neg_hi:[1,0,0]
	v_lshlrev_b32_e32 v42, 16, v33
	v_mul_f32_e32 v3, 0xbfb8aa3b, v42
	v_exp_f32_e32 v3, v3
	v_and_b32_e32 v43, 0xffff0000, v33
	v_mov_b32_e32 v29, v40
	v_add_f32_e32 v3, 1.0, v3
	v_rcp_f32_e32 v44, v3
	v_mul_f32_e32 v3, 0xbfb8aa3b, v43
	v_exp_f32_e32 v3, v3
	s_nop 0
	v_add_f32_e32 v3, 1.0, v3
	v_rcp_f32_e32 v45, v3
	v_and_b32_e32 v3, 0xffff0000, v28
	v_pk_mul_f32 v[42:43], v[44:45], v[42:43]
	v_lshlrev_b32_e32 v44, 16, v2
	v_and_b32_e32 v45, 0xffff0000, v2
	v_lshlrev_b32_e32 v2, 16, v28
	v_pk_fma_f32 v[2:3], v[6:7], v[2:3], v[44:45] neg_lo:[1,0,0] neg_hi:[1,0,0]
	v_mov_b32_e32 v45, v41
	v_mov_b32_e32 v28, v2
	v_pk_mul_f32 v[28:29], v[28:29], v[28:29]
	v_mov_b32_e32 v44, v3
	v_pk_fma_f32 v[28:29], v[44:45], v[44:45], v[28:29]
	v_lshlrev_b32_e32 v44, 16, v32
	v_add_f32_e32 v28, v28, v29
	v_add_f32_e32 v28, v31, v28
	v_add_f32_e32 v28, v30, v28
	v_and_b32_e32 v45, 0xffff0000, v32
	v_mul_f32_e32 v32, 0xbfb8aa3b, v44
	v_add_f32_dpp v28, v28, v28 quad_perm:[1,0,3,2] row_mask:0xf bank_mask:0xf bound_ctrl:1
	v_mul_f32_e32 v33, 0xbfb8aa3b, v45
	v_exp_f32_e32 v32, v32
	v_add_f32_dpp v28, v28, v28 quad_perm:[2,3,0,1] row_mask:0xf bank_mask:0xf bound_ctrl:1
	v_exp_f32_e32 v33, v33
	v_add_f32_e32 v32, 1.0, v32
	v_add_f32_dpp v28, v28, v28 row_half_mirror row_mask:0xf bank_mask:0xf bound_ctrl:1
	v_add_f32_e32 v33, 1.0, v33
	v_rcp_f32_e32 v32, v32
	v_add_f32_dpp v28, v28, v28 row_mirror row_mask:0xf bank_mask:0xf bound_ctrl:1
	v_fmamk_f32 v28, v28, 0x3c000000, v245
	v_cmp_gt_f32_e32 vcc, s75, v28
	v_mul_f32_e32 v29, 0x4b800000, v28
	v_rcp_f32_e32 v33, v33
	v_cndmask_b32_e32 v28, v28, v29, vcc
	v_rsq_f32_e32 v28, v28
	v_pk_mul_f32 v[32:33], v[32:33], v[44:45]
	v_mul_f32_e32 v29, 0x45800000, v28
	v_cndmask_b32_e32 v28, v28, v29, vcc
	v_pk_mul_f32 v[2:3], v[2:3], v[28:29] op_sel_hi:[1,0]
	v_pk_mul_f32 v[30:31], v[40:41], v[28:29] op_sel_hi:[1,0]
	v_pk_mul_f32 v[2:3], v[8:9], v[2:3]
	v_pk_mul_f32 v[30:31], v[10:11], v[30:31]
	v_pk_mul_f32 v[4:5], v[4:5], v[28:29] op_sel_hi:[1,0]
	v_pk_mul_f32 v[2:3], v[32:33], v[2:3]
	v_pk_mul_f32 v[30:31], v[42:43], v[30:31]
	v_pk_mul_f32 v[4:5], v[12:13], v[4:5]
	v_cvt_pk_bf16_f32 v2, v2, v3
	v_cvt_pk_bf16_f32 v3, v30, v31
	v_pk_mul_f32 v[4:5], v[38:39], v[4:5]
	v_lshlrev_b32_e32 v30, 16, v35
	v_cvt_pk_bf16_f32 v4, v4, v5
	v_mul_f32_e32 v5, 0xbfb8aa3b, v30
	v_exp_f32_e32 v5, v5
	v_and_b32_e32 v31, 0xffff0000, v35
	v_pk_mul_f32 v[28:29], v[36:37], v[28:29] op_sel_hi:[1,0]
	v_add_f32_e32 v5, 1.0, v5
	v_rcp_f32_e32 v32, v5
	v_mul_f32_e32 v5, 0xbfb8aa3b, v31
	v_exp_f32_e32 v5, v5
	v_pk_mul_f32 v[28:29], v[14:15], v[28:29]
	v_add_f32_e32 v5, 1.0, v5
	v_rcp_f32_e32 v33, v5
	s_nop 0
	v_pk_mul_f32 v[30:31], v[32:33], v[30:31]
	s_nop 0
	v_pk_mul_f32 v[28:29], v[30:31], v[28:29]
	s_nop 0
	v_cvt_pk_bf16_f32 v5, v28, v29
	v_lshl_add_u64 v[28:29], v[20:21], 0, v[0:1]
	v_lshl_add_u64 v[20:21], v[20:21], 0, s[42:43]
	global_store_dwordx4 v[28:29], v[2:5], off
	s_cbranch_scc1 .LBB0_709
	s_branch .LBB0_632
